# MP1: channel-map routine inner loop software-pipelined (next step's 8 row loads requested before the current step's FMAs; two register sets, counted vmcnt)
# speedup vs baseline: 1.0090x; 1.0073x over previous
; #define LAS __attribute__((address_space(3)))
; __device__ void p0_mmat(const Args& a, LAS unsigned char* lds) {
;     ...
;     for (int idx = blockIdx.x * NTHREADS + tid; idx < total; idx += gridDim.x * NTHREADS) {
;         const int d4 = idx & 63, cp = (idx >> 6) & 127, lg = idx >> 13;
;         const float* W = a.w_four + (size_t)lg * 128 * 128 + 4 * (d4 & 31);
;         const LAS float* tb = (d4 < 32) ? ct : st;
;         f32x4 acc = {0.f, 0.f, 0.f, 0.f};
; #pragma unroll 8
;         for (int c = 0; c < 128; ++c) acc += *(const f32x4*)(W + c * 128) * tb[(cp * c) & 127];
;         *(f32x4*)(MM + ((size_t)(lg * 128 + cp) * 256 + 4 * d4)) = acc * 0.08838834764831845f;
.LBB0_11:
	s_mov_b32 s100, 0
	v_lshl_add_u64 v[56:57], v[8:9], 0, s[12:13]
	global_load_dwordx4 v[24:27], v[56:57], off
	global_load_dwordx4 v[28:31], v[56:57], off offset:512
	global_load_dwordx4 v[32:35], v[56:57], off offset:1024
	global_load_dwordx4 v[36:39], v[56:57], off offset:1536
	global_load_dwordx4 v[40:43], v[56:57], off offset:2048
	global_load_dwordx4 v[44:47], v[56:57], off offset:2560
	global_load_dwordx4 v[48:51], v[56:57], off offset:3072
	global_load_dwordx4 v[52:55], v[56:57], off offset:3584
.Lmp_loop:
	s_add_u32 s12, s12, 0x1000
	v_lshl_add_u64 v[104:105], v[8:9], 0, s[12:13]
	global_load_dwordx4 v[72:75], v[104:105], off
	global_load_dwordx4 v[76:79], v[104:105], off offset:512
	global_load_dwordx4 v[80:83], v[104:105], off offset:1024
	global_load_dwordx4 v[84:87], v[104:105], off offset:1536
	global_load_dwordx4 v[88:91], v[104:105], off offset:2048
	global_load_dwordx4 v[92:95], v[104:105], off offset:2560
	global_load_dwordx4 v[96:99], v[104:105], off offset:3072
	global_load_dwordx4 v[100:103], v[104:105], off offset:3584
	v_add_u32_e32 v57, v17, v7
	v_add_u32_e32 v58, v18, v7
	v_and_b32_e32 v23, 0x78, v7
	v_add_u32_e32 v56, v15, v7
	v_add_u32_e32 v59, v19, v7
	v_add_u32_e32 v60, v20, v7
	v_add_u32_e32 v61, v21, v7
	v_add_u32_e32 v62, v22, v7
	v_and_b32_e32 v57, 0x7e, v57
	v_and_b32_e32 v58, 0x7f, v58
	v_lshl_add_u32 v23, v23, 2, v14
	v_and_b32_e32 v56, 0x7f, v56
	v_and_b32_e32 v59, 0x7c, v59
	v_and_b32_e32 v60, 0x7f, v60
	v_and_b32_e32 v61, 0x7e, v61
	v_and_b32_e32 v62, 0x7f, v62
	v_lshl_add_u32 v57, v57, 2, v14
	v_lshl_add_u32 v64, v58, 2, v14
	v_lshl_add_u32 v63, v56, 2, v14
	v_lshl_add_u32 v59, v59, 2, v14
	v_lshl_add_u32 v65, v60, 2, v14
	v_lshl_add_u32 v61, v61, 2, v14
	v_lshl_add_u32 v67, v62, 2, v14
	ds_read_b32 v56, v23
	ds_read_b32 v58, v63
	ds_read_b32 v60, v57
	ds_read_b32 v62, v64
	ds_read_b32 v64, v59
	ds_read_b32 v66, v65
	ds_read_b32 v68, v61
	ds_read_b32 v70, v67
	v_add_u32_e32 v7, v7, v16
	s_waitcnt vmcnt(15) lgkmcnt(7)
	v_pk_fma_f32 v[10:11], v[24:25], v[56:57], v[10:11] op_sel_hi:[1,0,1]
	v_pk_fma_f32 v[12:13], v[26:27], v[56:57], v[12:13] op_sel_hi:[1,0,1]
	s_waitcnt vmcnt(14) lgkmcnt(6)
	v_pk_fma_f32 v[10:11], v[28:29], v[58:59], v[10:11] op_sel_hi:[1,0,1]
	v_pk_fma_f32 v[12:13], v[30:31], v[58:59], v[12:13] op_sel_hi:[1,0,1]
	s_waitcnt vmcnt(13) lgkmcnt(5)
	v_pk_fma_f32 v[10:11], v[32:33], v[60:61], v[10:11] op_sel_hi:[1,0,1]
	v_pk_fma_f32 v[12:13], v[34:35], v[60:61], v[12:13] op_sel_hi:[1,0,1]
	s_waitcnt vmcnt(12) lgkmcnt(4)
	v_pk_fma_f32 v[10:11], v[36:37], v[62:63], v[10:11] op_sel_hi:[1,0,1]
	v_pk_fma_f32 v[12:13], v[38:39], v[62:63], v[12:13] op_sel_hi:[1,0,1]
	s_waitcnt vmcnt(11) lgkmcnt(3)
	v_pk_fma_f32 v[10:11], v[40:41], v[64:65], v[10:11] op_sel_hi:[1,0,1]
	v_pk_fma_f32 v[12:13], v[42:43], v[64:65], v[12:13] op_sel_hi:[1,0,1]
	s_waitcnt vmcnt(10) lgkmcnt(2)
	v_pk_fma_f32 v[10:11], v[44:45], v[66:67], v[10:11] op_sel_hi:[1,0,1]
	v_pk_fma_f32 v[12:13], v[46:47], v[66:67], v[12:13] op_sel_hi:[1,0,1]
	s_waitcnt vmcnt(9) lgkmcnt(1)
	v_pk_fma_f32 v[10:11], v[48:49], v[68:69], v[10:11] op_sel_hi:[1,0,1]
	v_pk_fma_f32 v[12:13], v[50:51], v[68:69], v[12:13] op_sel_hi:[1,0,1]
	s_waitcnt vmcnt(8) lgkmcnt(0)
	v_pk_fma_f32 v[10:11], v[52:53], v[70:71], v[10:11] op_sel_hi:[1,0,1]
	v_pk_fma_f32 v[12:13], v[54:55], v[70:71], v[12:13] op_sel_hi:[1,0,1]
	s_add_u32 s12, s12, 0x1000
	s_and_b32 s12, s12, 0xffff
	v_lshl_add_u64 v[56:57], v[8:9], 0, s[12:13]
	global_load_dwordx4 v[24:27], v[56:57], off
	global_load_dwordx4 v[28:31], v[56:57], off offset:512
	global_load_dwordx4 v[32:35], v[56:57], off offset:1024
	global_load_dwordx4 v[36:39], v[56:57], off offset:1536
	global_load_dwordx4 v[40:43], v[56:57], off offset:2048
	global_load_dwordx4 v[44:47], v[56:57], off offset:2560
	global_load_dwordx4 v[48:51], v[56:57], off offset:3072
	global_load_dwordx4 v[52:55], v[56:57], off offset:3584
	v_add_u32_e32 v57, v17, v7
	v_add_u32_e32 v58, v18, v7
	v_and_b32_e32 v23, 0x78, v7
	v_add_u32_e32 v56, v15, v7
	v_add_u32_e32 v59, v19, v7
	v_add_u32_e32 v60, v20, v7
	v_add_u32_e32 v61, v21, v7
	v_add_u32_e32 v62, v22, v7
	v_and_b32_e32 v57, 0x7e, v57
	v_and_b32_e32 v58, 0x7f, v58
	v_lshl_add_u32 v23, v23, 2, v14
	v_and_b32_e32 v56, 0x7f, v56
	v_and_b32_e32 v59, 0x7c, v59
	v_and_b32_e32 v60, 0x7f, v60
	v_and_b32_e32 v61, 0x7e, v61
	v_and_b32_e32 v62, 0x7f, v62
	v_lshl_add_u32 v57, v57, 2, v14
	v_lshl_add_u32 v64, v58, 2, v14
	v_lshl_add_u32 v63, v56, 2, v14
	v_lshl_add_u32 v59, v59, 2, v14
	v_lshl_add_u32 v65, v60, 2, v14
	v_lshl_add_u32 v61, v61, 2, v14
	v_lshl_add_u32 v67, v62, 2, v14
	ds_read_b32 v56, v23
	ds_read_b32 v58, v63
	ds_read_b32 v60, v57
	ds_read_b32 v62, v64
	ds_read_b32 v64, v59
	ds_read_b32 v66, v65
	ds_read_b32 v68, v61
	ds_read_b32 v70, v67
	v_add_u32_e32 v7, v7, v16
	s_waitcnt vmcnt(15) lgkmcnt(7)
	v_pk_fma_f32 v[10:11], v[72:73], v[56:57], v[10:11] op_sel_hi:[1,0,1]
	v_pk_fma_f32 v[12:13], v[74:75], v[56:57], v[12:13] op_sel_hi:[1,0,1]
	s_waitcnt vmcnt(14) lgkmcnt(6)
	v_pk_fma_f32 v[10:11], v[76:77], v[58:59], v[10:11] op_sel_hi:[1,0,1]
	v_pk_fma_f32 v[12:13], v[78:79], v[58:59], v[12:13] op_sel_hi:[1,0,1]
	s_waitcnt vmcnt(13) lgkmcnt(5)
	v_pk_fma_f32 v[10:11], v[80:81], v[60:61], v[10:11] op_sel_hi:[1,0,1]
	v_pk_fma_f32 v[12:13], v[82:83], v[60:61], v[12:13] op_sel_hi:[1,0,1]
	s_waitcnt vmcnt(12) lgkmcnt(4)
	v_pk_fma_f32 v[10:11], v[84:85], v[62:63], v[10:11] op_sel_hi:[1,0,1]
	v_pk_fma_f32 v[12:13], v[86:87], v[62:63], v[12:13] op_sel_hi:[1,0,1]
	s_waitcnt vmcnt(11) lgkmcnt(3)
	v_pk_fma_f32 v[10:11], v[88:89], v[64:65], v[10:11] op_sel_hi:[1,0,1]
	v_pk_fma_f32 v[12:13], v[90:91], v[64:65], v[12:13] op_sel_hi:[1,0,1]
	s_waitcnt vmcnt(10) lgkmcnt(2)
	v_pk_fma_f32 v[10:11], v[92:93], v[66:67], v[10:11] op_sel_hi:[1,0,1]
	v_pk_fma_f32 v[12:13], v[94:95], v[66:67], v[12:13] op_sel_hi:[1,0,1]
	s_waitcnt vmcnt(9) lgkmcnt(1)
	v_pk_fma_f32 v[10:11], v[96:97], v[68:69], v[10:11] op_sel_hi:[1,0,1]
	v_pk_fma_f32 v[12:13], v[98:99], v[68:69], v[12:13] op_sel_hi:[1,0,1]
	s_waitcnt vmcnt(8) lgkmcnt(0)
	v_pk_fma_f32 v[10:11], v[100:101], v[70:71], v[10:11] op_sel_hi:[1,0,1]
	v_pk_fma_f32 v[12:13], v[102:103], v[70:71], v[12:13] op_sel_hi:[1,0,1]
	s_add_i32 s100, s100, 1
	s_cmp_lt_u32 s100, 8
	s_cbranch_scc1 .Lmp_loop
	s_waitcnt vmcnt(0)
	v_bfe_u32 v7, v1, 6, 7
	v_lshl_or_b32 v6, v6, 7, v7
	v_ashrrev_i32_e32 v7, 31, v6
	v_add_u32_e32 v1, s9, v1
	v_lshlrev_b64 v[6:7], 10, v[6:7]
	v_cmp_lt_i32_e32 vcc, s34, v1
	v_pk_mul_f32 v[12:13], v[12:13], s[10:11] op_sel_hi:[1,0]
	v_pk_mul_f32 v[10:11], v[10:11], s[10:11] op_sel_hi:[1,0]
	v_lshl_add_u64 v[6:7], v[4:5], 0, v[6:7]
	s_or_b64 s[6:7], vcc, s[6:7]
	v_add_u32_e32 v2, s11, v2
	global_store_dwordx4 v[6:7], v[10:13], off
	s_andn2_b64 exec, exec, s[6:7]
	s_cbranch_execnz .LBB0_10
